# weight-tile stores transposed through LDS into full-line writes; prompt attention tasks moved off the scan-block worker waves
# speedup vs baseline: 1.0199x; 1.0199x over previous
; __device__ __forceinline__ int acc_row(int reg, int hh) { return (reg & 3) + 8 * (reg >> 2) + 4 * hh; }
; #define REP(k) for (int rep_ = 0; rep_ < 1 + ((PROBE_MASK >> (k)) & 1); ++rep_)
; __device__ __forceinline__ void attn_prompt_task(const P& p, int l, int s, int qb, int h, LAS unsigned char* ldsw, int lane) {
;     ...
;     for (int kt = 0; kt < 5; ++kt)
; #pragma unroll
;         for (int reg = 0; reg < 16; ++reg) {
;             const int kk = 32 * kt + acc_row(reg, hh);
;             const bool valid = (kk >= r) && (kk <= r + 128) && (q0 - 128 + kk >= 0);
;             const float v = valid ? st[kt][reg] * 0.125f : -3.0e38f;
;             st[kt][reg] = v; m = fmaxf(m, v);
;         }
; __global__ void __launch_bounds__(512, 2) mega(Args a) {
;     ...
;             } else {
;                 const int wpb = 8 - nrole;
;                 const int widx = scan_block ? bx * wpb + (wave - nrole) : nsb * wpb + (bx - nsb) * 8 + wave, nwork = nsb * wpb + (G - nsb) * 8;
;                 REP(14) for (int task = widx; task < 8192; task += nwork) scan_task(p, l, 512 + task, lane);
;                 REP(15) for (int task = widx; task < NDEC * 4; task += nwork) attn_task(p, l, NPROMPT + (task >> 2), task & 3, lane);
;                 REP(16) for (int task = widx; task < 4096; task += nwork) attn_prompt_task(p, l, task >> 11, (task >> 4) & 127, task & 15, lds + 106496 + wave * 2560, lane);
;                 if (l + 1 < DEPTH && widx >= NDEC * 4) for (int task = widx - NDEC * 4; task < WT_LAYER; task += nwork - NDEC * 4) wT_wave_task(p, (l + 1) * WT_LAYER + task, lane);
.LBB0_1417:
	v_readlane_b32 s4, v249, 12
	v_readlane_b32 s8, v249, 16
	v_readlane_b32 s9, v249, 17
	v_readlane_b32 s5, v249, 13
	v_readlane_b32 s6, v249, 14
	v_readlane_b32 s7, v249, 15
	v_readlane_b32 s10, v249, 18
	v_readlane_b32 s11, v249, 19
	v_readlane_b32 s12, v249, 20
	v_readlane_b32 s13, v249, 21
	v_readlane_b32 s14, v249, 22
	v_readlane_b32 s15, v249, 23
	v_readlane_b32 s16, v249, 24
	v_readlane_b32 s17, v249, 25
	v_readlane_b32 s18, v249, 26
	v_readlane_b32 s19, v249, 27
	s_mov_b64 s[80:81], s[8:9]
	s_mov_b64 s[78:79], s[6:7]
	s_mov_b64 s[76:77], s[4:5]
	v_readlane_b32 s8, v250, 30
	v_readlane_b32 s16, v250, 38
	v_readlane_b32 s17, v250, 39
	v_readlane_b32 s20, v250, 42
	v_readlane_b32 s60, v249, 62
	s_cmpk_gt_i32 s93, 0x1ff
	v_readlane_b32 s18, v250, 40
	v_readlane_b32 s19, v250, 41
	v_readlane_b32 s70, v250, 8
	v_readlane_b32 s71, v250, 9
	v_readlane_b32 s72, v250, 10
	v_readlane_b32 s73, v250, 11
	v_readlane_b32 s74, v250, 12
	v_readlane_b32 s75, v250, 13
	v_readlane_b32 s16, v252, 3
	s_mov_b32 s17, 0xfe967699
	s_mov_b32 s20, 0x3e000000
	v_readlane_b32 s9, v250, 31
	v_readlane_b32 s10, v250, 32
	v_readlane_b32 s11, v250, 33
	v_readlane_b32 s12, v250, 34
	v_readlane_b32 s13, v250, 35
	v_readlane_b32 s14, v250, 36
	v_readlane_b32 s15, v250, 37
	v_readlane_b32 s21, v250, 43
	v_readlane_b32 s22, v250, 44
	v_readlane_b32 s23, v250, 45
	v_readlane_b32 s61, v249, 63
	v_readlane_b32 s62, v250, 0
	v_readlane_b32 s63, v250, 1
	v_readlane_b32 s64, v250, 2
	v_readlane_b32 s65, v250, 3
	v_readlane_b32 s66, v250, 4
	v_readlane_b32 s67, v250, 5
	v_readlane_b32 s68, v250, 6
	v_readlane_b32 s69, v250, 7
	s_cbranch_scc0 .LBB0_1420
	v_lshrrev_b32_e32 v1, 5, v161
	s_mul_i32 s0, s55, 0xa00
	v_and_b32_e32 v95, 31, v178
	v_lshlrev_b32_e32 v50, 2, v1
	s_add_i32 s0, s0, 0
	v_or_b32_e32 v2, 0x80, v95
	v_or_b32_e32 v3, 0x81, v50
	s_add_i32 s6, s0, 0x1a000
	v_cmp_gt_u32_e64 s[0:1], v3, v2
	v_or_b32_e32 v3, 0x83, v50
	v_or_b32_e32 v4, 0x82, v50
	v_writelane_b32 v248, s0, 2
	v_lshlrev_b32_e32 v46, 3, v1
	v_lshlrev_b32_e32 v162, 4, v1
	v_writelane_b32 v248, s1, 3
	v_cmp_gt_u32_e64 s[0:1], v3, v2
	v_or_b32_e32 v3, 0x89, v50
	v_or_b32_e32 v1, 1, v50
	v_writelane_b32 v248, s0, 4
	v_or_b32_e32 v97, 2, v50
	v_or_b32_e32 v99, 3, v50
	v_writelane_b32 v248, s1, 5
	v_cmp_gt_u32_e64 s[0:1], v4, v2
	v_or_b32_e32 v4, 0x88, v50
	v_or_b32_e32 v101, 8, v50
	v_writelane_b32 v248, s0, 6
	v_or_b32_e32 v146, 9, v50
	v_or_b32_e32 v147, 10, v50
	v_writelane_b32 v248, s1, 7
	v_cmp_gt_u32_e64 s[0:1], v3, v2
	v_or_b32_e32 v3, 0x8b, v50
	v_cmp_gt_u32_e64 s[46:47], v3, v2
	v_writelane_b32 v248, s0, 8
	v_or_b32_e32 v3, 0x91, v50
	v_cmp_gt_u32_e64 s[56:57], v3, v2
	v_writelane_b32 v248, s1, 9
	v_cmp_gt_u32_e64 s[0:1], v4, v2
	v_or_b32_e32 v4, 0x8a, v50
	v_cmp_gt_u32_e64 s[48:49], v4, v2
	v_or_b32_e32 v4, 0x90, v50
	v_cmp_gt_u32_e64 s[38:39], v4, v2
	v_or_b32_e32 v3, 0x93, v50
	v_or_b32_e32 v4, 0x92, v50
	v_cmp_gt_u32_e64 s[40:41], v3, v2
	v_cmp_gt_u32_e64 s[42:43], v4, v2
	v_or_b32_e32 v3, 0x99, v50
	v_or_b32_e32 v4, 0x98, v50
	v_writelane_b32 v248, s0, 10
	v_cmp_gt_u32_e64 s[44:45], v3, v2
	v_cmp_gt_u32_e64 s[96:97], v4, v2
	v_or_b32_e32 v3, 0x9b, v50
	v_or_b32_e32 v4, 0x9a, v50
	v_writelane_b32 v248, s1, 11
	v_cmp_gt_u32_e64 s[0:1], v3, v2
	v_cmp_gt_u32_e64 s[4:5], v4, v2
	v_mul_u32_u24_e32 v2, 0x50, v95
	v_and_b32_e32 v3, 64, v201
	v_add3_u32 v157, s6, v2, v46
	v_xor_b32_e32 v2, 32, v201
	v_add_u32_e32 v3, 64, v3
	v_cmp_lt_i32_e32 vcc, v2, v3
	v_or_b32_e32 v148, 11, v50
	v_or_b32_e32 v149, 16, v50
	v_or_b32_e32 v150, 17, v50
	v_or_b32_e32 v151, 18, v50
	v_or_b32_e32 v152, 19, v50
	v_or_b32_e32 v153, 24, v50
	v_or_b32_e32 v154, 25, v50
	v_or_b32_e32 v155, 26, v50
	v_or_b32_e32 v156, 27, v50
	v_cndmask_b32_e32 v2, v201, v2, vcc
	v_lshl_add_u64 v[48:49], s[72:73], 0, v[162:163]
	v_cmp_ge_u32_e64 s[22:23], v50, v95
	v_cmp_ge_u32_e64 s[24:25], v1, v95
	v_cmp_ge_u32_e64 s[26:27], v97, v95
	v_cmp_ge_u32_e64 s[36:37], v99, v95
	v_cmp_ge_u32_e64 s[60:61], v101, v95
	v_cmp_ge_u32_e64 s[62:63], v146, v95
	v_cmp_ge_u32_e64 s[64:65], v147, v95
	v_cmp_ge_u32_e64 s[66:67], v148, v95
	v_cmp_ge_u32_e64 s[68:69], v149, v95
	v_cmp_ge_u32_e64 s[72:73], v150, v95
	v_cmp_ge_u32_e64 s[76:77], v151, v95
	v_cmp_ge_u32_e64 s[80:81], v152, v95
	v_cmp_ge_u32_e64 s[82:83], v153, v95
	v_cmp_ge_u32_e64 s[84:85], v154, v95
	v_cmp_ge_u32_e64 s[86:87], v155, v95
	v_cmp_ge_u32_e64 s[88:89], v156, v95
	v_or_b32_e32 v1, 33, v50
	v_or_b32_e32 v52, 32, v50
	v_or_b32_e32 v47, 35, v50
	v_or_b32_e32 v54, 34, v50
	v_or_b32_e32 v51, 41, v50
	v_or_b32_e32 v56, 40, v50
	v_or_b32_e32 v53, 43, v50
	v_or_b32_e32 v58, 42, v50
	v_or_b32_e32 v55, 49, v50
	v_or_b32_e32 v60, 48, v50
	v_or_b32_e32 v57, 51, v50
	v_or_b32_e32 v62, 50, v50
	v_or_b32_e32 v59, 57, v50
	v_or_b32_e32 v64, 56, v50
	v_or_b32_e32 v61, 59, v50
	v_or_b32_e32 v66, 58, v50
	v_or_b32_e32 v63, 0x41, v50
	v_or_b32_e32 v68, 64, v50
	v_or_b32_e32 v65, 0x43, v50
	v_or_b32_e32 v70, 0x42, v50
	v_or_b32_e32 v67, 0x49, v50
	v_or_b32_e32 v72, 0x48, v50
	v_or_b32_e32 v69, 0x4b, v50
	v_or_b32_e32 v74, 0x4a, v50
	v_or_b32_e32 v71, 0x51, v50
	v_or_b32_e32 v76, 0x50, v50
	v_or_b32_e32 v73, 0x53, v50
	v_or_b32_e32 v78, 0x52, v50
	v_or_b32_e32 v75, 0x59, v50
	v_or_b32_e32 v80, 0x58, v50
	v_or_b32_e32 v77, 0x5b, v50
	v_or_b32_e32 v82, 0x5a, v50
	v_or_b32_e32 v79, 0x61, v50
	v_or_b32_e32 v84, 0x60, v50
	v_or_b32_e32 v81, 0x63, v50
	v_or_b32_e32 v86, 0x62, v50
	v_or_b32_e32 v83, 0x69, v50
	v_or_b32_e32 v88, 0x68, v50
	v_or_b32_e32 v85, 0x6b, v50
	v_or_b32_e32 v90, 0x6a, v50
	v_or_b32_e32 v87, 0x71, v50
	v_or_b32_e32 v92, 0x70, v50
	v_or_b32_e32 v89, 0x73, v50
	v_or_b32_e32 v94, 0x72, v50
	v_or_b32_e32 v91, 0x79, v50
	v_or_b32_e32 v96, 0x78, v50
	v_or_b32_e32 v93, 0x7b, v50
	v_or_b32_e32 v98, 0x7a, v50
	v_cmp_gt_u32_e64 s[90:91], v50, v95
	v_lshlrev_b32_e32 v100, 13, v95
	v_lshlrev_b32_e32 v158, 2, v2
	s_add_i32 s6, s93, 0xfffffe00

; __device__ __forceinline__ void wT_wave_task(const P& p, int id, int lane) {
;     const WTile w = wT_tile(p, id);
;     const int n = w.n0 + lane; const bool ok = n < w.N;
;     const float* q = w.W + (size_t)w.k0 * w.N + (ok ? n : 0);
;     float v[64];
; #pragma unroll
;     for (int kk = 0; kk < 64; ++kk) { v[kk] = *q; q += w.N; }
;     bf16* o = w.Bt + (size_t)n * w.K + w.k0;
.LBB0_1424:
	s_ashr_i32 s5, s4, 31
	v_add_u32_e32 v1, s9, v161
	s_mul_hi_u32 s8, s4, s34
	s_mul_i32 s9, s5, s34
	s_add_i32 s9, s8, s9
	s_mul_i32 s8, s4, s34
	s_lshl_b64 s[8:9], s[8:9], 2
	v_cmp_gt_i32_e32 vcc, s34, v1
	s_add_u32 s8, s10, s8
	s_addc_u32 s9, s11, s9
	v_cndmask_b32_e32 v2, 0, v1, vcc
	v_ashrrev_i32_e32 v3, 31, v2
	v_lshl_add_u64 v[2:3], v[2:3], 2, s[8:9]
	s_lshl_b64 s[8:9], s[34:35], 2
	v_lshl_add_u64 v[4:5], v[2:3], 0, s[8:9]
	v_lshl_add_u64 v[6:7], v[4:5], 0, s[8:9]
	v_lshl_add_u64 v[8:9], v[6:7], 0, s[8:9]
	s_waitcnt lgkmcnt(1)
	v_lshl_add_u64 v[10:11], v[8:9], 0, s[8:9]
	s_waitcnt lgkmcnt(0)
	v_lshl_add_u64 v[12:13], v[10:11], 0, s[8:9]
	v_lshl_add_u64 v[14:15], v[12:13], 0, s[8:9]
	v_lshl_add_u64 v[16:17], v[14:15], 0, s[8:9]
	global_load_dword v18, v[2:3], off
	s_nop 0
	global_load_dword v4, v[4:5], off
	s_nop 0
	global_load_dword v5, v[6:7], off
	s_nop 0
	global_load_dword v8, v[8:9], off
	s_nop 0
	global_load_dword v9, v[10:11], off
	s_nop 0
	global_load_dword v10, v[12:13], off
	global_load_dword v11, v[14:15], off
	s_nop 0
	global_load_dword v12, v[16:17], off
	v_lshl_add_u64 v[2:3], v[16:17], 0, s[8:9]
	global_load_dword v13, v[2:3], off
	v_lshl_add_u64 v[2:3], v[2:3], 0, s[8:9]
	global_load_dword v14, v[2:3], off
	v_lshl_add_u64 v[2:3], v[2:3], 0, s[8:9]
	global_load_dword v15, v[2:3], off
	v_lshl_add_u64 v[2:3], v[2:3], 0, s[8:9]
	global_load_dword v16, v[2:3], off
	v_lshl_add_u64 v[2:3], v[2:3], 0, s[8:9]
	global_load_dword v17, v[2:3], off
	v_lshl_add_u64 v[2:3], v[2:3], 0, s[8:9]
	global_load_dword v19, v[2:3], off
	v_lshl_add_u64 v[2:3], v[2:3], 0, s[8:9]
	global_load_dword v20, v[2:3], off
	v_lshl_add_u64 v[2:3], v[2:3], 0, s[8:9]
	global_load_dword v21, v[2:3], off
	v_lshl_add_u64 v[2:3], v[2:3], 0, s[8:9]
	global_load_dword v22, v[2:3], off
	v_lshl_add_u64 v[2:3], v[2:3], 0, s[8:9]
	global_load_dword v23, v[2:3], off
	v_lshl_add_u64 v[2:3], v[2:3], 0, s[8:9]
	global_load_dword v24, v[2:3], off
	v_lshl_add_u64 v[2:3], v[2:3], 0, s[8:9]
	global_load_dword v25, v[2:3], off
	v_lshl_add_u64 v[2:3], v[2:3], 0, s[8:9]
	global_load_dword v26, v[2:3], off
	v_lshl_add_u64 v[2:3], v[2:3], 0, s[8:9]
	global_load_dword v27, v[2:3], off
	v_lshl_add_u64 v[2:3], v[2:3], 0, s[8:9]
	global_load_dword v28, v[2:3], off
	v_lshl_add_u64 v[2:3], v[2:3], 0, s[8:9]
	global_load_dword v29, v[2:3], off
	v_lshl_add_u64 v[2:3], v[2:3], 0, s[8:9]
	global_load_dword v30, v[2:3], off
	v_lshl_add_u64 v[2:3], v[2:3], 0, s[8:9]
	global_load_dword v31, v[2:3], off
	v_lshl_add_u64 v[2:3], v[2:3], 0, s[8:9]
	global_load_dword v32, v[2:3], off
	v_lshl_add_u64 v[2:3], v[2:3], 0, s[8:9]
	global_load_dword v33, v[2:3], off
	v_lshl_add_u64 v[2:3], v[2:3], 0, s[8:9]
	global_load_dword v34, v[2:3], off
	v_lshl_add_u64 v[2:3], v[2:3], 0, s[8:9]
	global_load_dword v35, v[2:3], off
	v_lshl_add_u64 v[2:3], v[2:3], 0, s[8:9]
	global_load_dword v36, v[2:3], off
	v_lshl_add_u64 v[2:3], v[2:3], 0, s[8:9]
	global_load_dword v37, v[2:3], off
	v_lshl_add_u64 v[2:3], v[2:3], 0, s[8:9]
	global_load_dword v38, v[2:3], off
	v_lshl_add_u64 v[2:3], v[2:3], 0, s[8:9]
	global_load_dword v39, v[2:3], off
	v_lshl_add_u64 v[2:3], v[2:3], 0, s[8:9]
	global_load_dword v40, v[2:3], off
	v_lshl_add_u64 v[2:3], v[2:3], 0, s[8:9]
	global_load_dword v41, v[2:3], off
	v_lshl_add_u64 v[2:3], v[2:3], 0, s[8:9]
	global_load_dword v42, v[2:3], off
	v_lshl_add_u64 v[2:3], v[2:3], 0, s[8:9]
	global_load_dword v43, v[2:3], off
	v_lshl_add_u64 v[2:3], v[2:3], 0, s[8:9]
	global_load_dword v44, v[2:3], off
	v_lshl_add_u64 v[2:3], v[2:3], 0, s[8:9]
	global_load_dword v45, v[2:3], off
	v_lshl_add_u64 v[2:3], v[2:3], 0, s[8:9]
	global_load_dword v46, v[2:3], off
	v_lshl_add_u64 v[2:3], v[2:3], 0, s[8:9]
	global_load_dword v47, v[2:3], off
	v_lshl_add_u64 v[2:3], v[2:3], 0, s[8:9]
	global_load_dword v48, v[2:3], off
	v_lshl_add_u64 v[2:3], v[2:3], 0, s[8:9]
	global_load_dword v49, v[2:3], off
	v_lshl_add_u64 v[2:3], v[2:3], 0, s[8:9]
	global_load_dword v50, v[2:3], off
	v_lshl_add_u64 v[2:3], v[2:3], 0, s[8:9]
	global_load_dword v51, v[2:3], off
	v_lshl_add_u64 v[2:3], v[2:3], 0, s[8:9]
	global_load_dword v52, v[2:3], off
	v_lshl_add_u64 v[2:3], v[2:3], 0, s[8:9]
	global_load_dword v53, v[2:3], off
	v_lshl_add_u64 v[2:3], v[2:3], 0, s[8:9]
	global_load_dword v54, v[2:3], off
	v_lshl_add_u64 v[2:3], v[2:3], 0, s[8:9]
	global_load_dword v55, v[2:3], off
	v_lshl_add_u64 v[2:3], v[2:3], 0, s[8:9]
	global_load_dword v56, v[2:3], off
	v_lshl_add_u64 v[2:3], v[2:3], 0, s[8:9]
	global_load_dword v57, v[2:3], off
	v_lshl_add_u64 v[2:3], v[2:3], 0, s[8:9]
	global_load_dword v58, v[2:3], off
	v_lshl_add_u64 v[2:3], v[2:3], 0, s[8:9]
	global_load_dword v59, v[2:3], off
	v_lshl_add_u64 v[2:3], v[2:3], 0, s[8:9]
	global_load_dword v60, v[2:3], off
	v_lshl_add_u64 v[2:3], v[2:3], 0, s[8:9]
	global_load_dword v61, v[2:3], off
	v_lshl_add_u64 v[2:3], v[2:3], 0, s[8:9]
	global_load_dword v62, v[2:3], off
	v_lshl_add_u64 v[2:3], v[2:3], 0, s[8:9]
	global_load_dword v63, v[2:3], off
	v_lshl_add_u64 v[2:3], v[2:3], 0, s[8:9]
	global_load_dword v64, v[2:3], off
	v_lshl_add_u64 v[2:3], v[2:3], 0, s[8:9]
	global_load_dword v65, v[2:3], off
	v_lshl_add_u64 v[2:3], v[2:3], 0, s[8:9]
	global_load_dword v66, v[2:3], off
	v_lshl_add_u64 v[2:3], v[2:3], 0, s[8:9]
	global_load_dword v67, v[2:3], off
	v_lshl_add_u64 v[2:3], v[2:3], 0, s[8:9]
	global_load_dword v68, v[2:3], off
	v_lshl_add_u64 v[2:3], v[2:3], 0, s[8:9]
	global_load_dword v69, v[2:3], off
	s_mul_i32 s100, s55, 0x2000
	v_readfirstlane_b32 s9, v1
	v_and_b32_e32 v6, 7, v161
	v_lshlrev_b32_e32 v6, 4, v6
	v_lshl_add_u32 v6, v161, 7, v6
	v_add_u32_e32 v6, s100, v6
	s_waitcnt vmcnt(62)
; __device__ __forceinline__ unsigned pk2(float lo, float hi) { f32x2_t v = {lo, hi}; bf16x2_t b = __builtin_convertvector(v, bf16x2_t); return __builtin_bit_cast(unsigned, b); }
; __device__ __forceinline__ void wT_wave_task(const P& p, int id, int lane) {
;     ...
;     bf16* o = w.Bt + (size_t)n * w.K + w.k0;
; #pragma unroll
;     for (int j = 0; j < 8; ++j) { u32x4v x; x.x = pk2(v[8 * j], v[8 * j + 1]); x.y = pk2(v[8 * j + 2], v[8 * j + 3]); x.z = pk2(v[8 * j + 4], v[8 * j + 5]); x.w = pk2(v[8 * j + 6], v[8 * j + 7]);
;         if (!ok) x = (u32x4v){0u, 0u, 0u, 0u};
;         *(u32x4v*)(o + 8 * j) = x; }
	v_cvt_pk_bf16_f32 v1, v18, v4
	s_waitcnt vmcnt(60)
	v_cvt_pk_bf16_f32 v3, v5, v8
	s_waitcnt vmcnt(58)
	v_cvt_pk_bf16_f32 v4, v9, v10
	s_waitcnt vmcnt(56)
	v_cvt_pk_bf16_f32 v5, v11, v12
	v_cndmask_b32_e32 v2, 0, v1, vcc
	v_cndmask_b32_e32 v3, 0, v3, vcc
	v_cndmask_b32_e32 v4, 0, v4, vcc
	v_cndmask_b32_e32 v5, 0, v5, vcc
	ds_write_b128 v6, v[2:5]
	s_waitcnt vmcnt(54)
	v_cvt_pk_bf16_f32 v1, v13, v14
	s_waitcnt vmcnt(52)
	v_cvt_pk_bf16_f32 v3, v15, v16
	s_waitcnt vmcnt(50)
	v_cvt_pk_bf16_f32 v4, v17, v19
	s_waitcnt vmcnt(48)
	v_cvt_pk_bf16_f32 v5, v20, v21
	v_cndmask_b32_e32 v2, 0, v1, vcc
	v_cndmask_b32_e32 v3, 0, v3, vcc
	v_cndmask_b32_e32 v4, 0, v4, vcc
	v_cndmask_b32_e32 v5, 0, v5, vcc
	v_xor_b32_e32 v7, 0x10, v6
	ds_write_b128 v7, v[2:5]
	s_waitcnt vmcnt(46)
	v_cvt_pk_bf16_f32 v1, v22, v23
	s_waitcnt vmcnt(44)
	v_cvt_pk_bf16_f32 v3, v24, v25
	s_waitcnt vmcnt(42)
	v_cvt_pk_bf16_f32 v4, v26, v27
	s_waitcnt vmcnt(40)
	v_cvt_pk_bf16_f32 v5, v28, v29
	v_cndmask_b32_e32 v2, 0, v1, vcc
	v_cndmask_b32_e32 v3, 0, v3, vcc
	v_cndmask_b32_e32 v4, 0, v4, vcc
	v_cndmask_b32_e32 v5, 0, v5, vcc
	v_xor_b32_e32 v7, 0x20, v6
	ds_write_b128 v7, v[2:5]
	s_waitcnt vmcnt(38)
	v_cvt_pk_bf16_f32 v1, v30, v31
	s_waitcnt vmcnt(36)
	v_cvt_pk_bf16_f32 v3, v32, v33
	s_waitcnt vmcnt(34)
	v_cvt_pk_bf16_f32 v4, v34, v35
	s_waitcnt vmcnt(32)
	v_cvt_pk_bf16_f32 v5, v36, v37
	v_cndmask_b32_e32 v2, 0, v1, vcc
	v_cndmask_b32_e32 v3, 0, v3, vcc
	v_cndmask_b32_e32 v4, 0, v4, vcc
	v_cndmask_b32_e32 v5, 0, v5, vcc
	v_xor_b32_e32 v7, 0x30, v6
	ds_write_b128 v7, v[2:5]
	s_waitcnt vmcnt(30)
	v_cvt_pk_bf16_f32 v1, v38, v39
	s_waitcnt vmcnt(28)
	v_cvt_pk_bf16_f32 v3, v40, v41
	s_waitcnt vmcnt(26)
	v_cvt_pk_bf16_f32 v4, v42, v43
	s_waitcnt vmcnt(24)
	v_cvt_pk_bf16_f32 v5, v44, v45
	v_cndmask_b32_e32 v2, 0, v1, vcc
	v_cndmask_b32_e32 v3, 0, v3, vcc
	v_cndmask_b32_e32 v4, 0, v4, vcc
	v_cndmask_b32_e32 v5, 0, v5, vcc
	v_xor_b32_e32 v7, 0x40, v6
	ds_write_b128 v7, v[2:5]
	s_waitcnt vmcnt(22)
	v_cvt_pk_bf16_f32 v1, v46, v47
	s_waitcnt vmcnt(20)
	v_cvt_pk_bf16_f32 v3, v48, v49
	s_waitcnt vmcnt(18)
	v_cvt_pk_bf16_f32 v4, v50, v51
	s_waitcnt vmcnt(16)
	v_cvt_pk_bf16_f32 v5, v52, v53
	v_cndmask_b32_e32 v2, 0, v1, vcc
	v_cndmask_b32_e32 v3, 0, v3, vcc
	v_cndmask_b32_e32 v4, 0, v4, vcc
	v_cndmask_b32_e32 v5, 0, v5, vcc
	v_xor_b32_e32 v7, 0x50, v6
	ds_write_b128 v7, v[2:5]
	s_waitcnt vmcnt(14)
	v_cvt_pk_bf16_f32 v1, v54, v55
	s_waitcnt vmcnt(12)
	v_cvt_pk_bf16_f32 v3, v56, v57
	s_waitcnt vmcnt(10)
	v_cvt_pk_bf16_f32 v4, v58, v59
	s_waitcnt vmcnt(8)
	v_cvt_pk_bf16_f32 v5, v60, v61
	v_cndmask_b32_e32 v2, 0, v1, vcc
	v_cndmask_b32_e32 v3, 0, v3, vcc
	v_cndmask_b32_e32 v4, 0, v4, vcc
	v_cndmask_b32_e32 v5, 0, v5, vcc
	v_xor_b32_e32 v7, 0x60, v6
	ds_write_b128 v7, v[2:5]
	s_waitcnt vmcnt(6)
	v_cvt_pk_bf16_f32 v1, v62, v63
	s_waitcnt vmcnt(4)
	v_cvt_pk_bf16_f32 v3, v64, v65
	s_waitcnt vmcnt(2)
	v_cvt_pk_bf16_f32 v4, v66, v67
	s_waitcnt vmcnt(0)
	v_cvt_pk_bf16_f32 v5, v68, v69
	v_cndmask_b32_e32 v2, 0, v1, vcc
	v_cndmask_b32_e32 v3, 0, v3, vcc
	v_cndmask_b32_e32 v4, 0, v4, vcc
	v_cndmask_b32_e32 v5, 0, v5, vcc
	v_xor_b32_e32 v7, 0x70, v6
	ds_write_b128 v7, v[2:5]
	v_lshrrev_b32_e32 v1, 3, v161
	v_and_b32_e32 v2, 7, v161
	v_xor_b32_e32 v3, v1, v2
	v_lshlrev_b32_e32 v3, 4, v3
	v_lshl_add_u32 v9, v1, 7, v3
	v_add_u32_e32 v9, s100, v9
	ds_read_b128 v[12:15], v9
	ds_read_b128 v[16:19], v9 offset:1024
	ds_read_b128 v[20:23], v9 offset:2048
	ds_read_b128 v[24:27], v9 offset:3072
	ds_read_b128 v[28:31], v9 offset:4096
	ds_read_b128 v[32:35], v9 offset:5120
	ds_read_b128 v[36:39], v9 offset:6144
	ds_read_b128 v[40:43], v9 offset:7168
	v_add_u32_e32 v3, s9, v1
	v_mul_lo_u32 v3, v3, s6
	v_lshl_add_u32 v2, v2, 3, s4
	v_add_lshl_u32 v8, v3, v2, 1
	s_mul_i32 s8, s6, 16
	s_waitcnt lgkmcnt(7)
	global_store_dwordx4 v8, v[12:15], s[0:1]
	v_add_u32_e32 v8, s8, v8
	s_waitcnt lgkmcnt(6)
	global_store_dwordx4 v8, v[16:19], s[0:1]
	v_add_u32_e32 v8, s8, v8
	s_waitcnt lgkmcnt(5)
	global_store_dwordx4 v8, v[20:23], s[0:1]
	v_add_u32_e32 v8, s8, v8
	s_waitcnt lgkmcnt(4)
	global_store_dwordx4 v8, v[24:27], s[0:1]
	v_add_u32_e32 v8, s8, v8
	s_waitcnt lgkmcnt(3)
	global_store_dwordx4 v8, v[28:31], s[0:1]
	v_add_u32_e32 v8, s8, v8
	s_waitcnt lgkmcnt(2)
	global_store_dwordx4 v8, v[32:35], s[0:1]
	v_add_u32_e32 v8, s8, v8
	s_waitcnt lgkmcnt(1)
	global_store_dwordx4 v8, v[36:39], s[0:1]
	v_add_u32_e32 v8, s8, v8
	s_waitcnt lgkmcnt(0)
	global_store_dwordx4 v8, v[40:43], s[0:1]
	v_readlane_b32 s100, v252, 3
	s_add_i32 s93, s93, s100
	s_add_i32 s100, s93, 0xfffffe00
	s_cmp_lt_i32 s100, s101
	s_cbranch_scc0 .LBB0_1421
